# diff_attn main loop: K staging LDS writes early (vmcnt(2)), V staging writes after the PV MFMAs for maximum distance from their global loads (stacked on v17)
# baseline (speedup 1.0000x reference)
; #define LAS __attribute__((address_space(3)))
; #define MFMA32(a, b, c) __builtin_amdgcn_mfma_f32_32x32x16_bf16((a), (b), (c), 0, 0, 0)
; DI f32x16 zero16() { f32x16 z; for (int i = 0; i < 16; ++i) z[i] = 0.f; return z; }
; DI void diff_attn_phase(int wv, LAS unsigned char* lds, const bf16_t* qk, const bf16_t* vt, bf16_t* ob, const float* lq1, const float* lk1, const float* lq2, const float* lk2,
;                         const float* subg, int layer_idx) {
;     ...
;         for (int t = 0; t < tmain; ++t) {
;             const int key0 = t * 64;
;             const bool more = true;
;             if (more) {
; #pragma unroll
;                 for (int i = 0; i < 2; ++i) gk[i] = *(const u32x4*)(kg + (size_t)(key0 + 64 + i * 32) * 2048); }
;             LAS unsigned char* buf = lds + (t & 1) * DA_BUF;
;             {
;                 f32x16 S0 = zero16(), S1 = zero16();
;                 {
;                     bf16x8 kf[2][4];
; #pragma unroll
;                     for (int sub = 0; sub < 2; ++sub)
; #pragma unroll
;                         for (int ks = 0; ks < 4; ++ks) kf[sub][ks] = *(const LAS bf16x8*)(buf + koff + sub * 32 * DA_KP + ks * 32);
; #pragma unroll
;                     for (int ks = 0; ks < 4; ++ks) { const bf16x8 qfr = *(const LAS bf16x8*)(qlds + ks * 1024); S0 = MFMA32(kf[0][ks], qfr, S0); S1 = MFMA32(kf[1][ks], qfr, S1); }
;                 }
;                 __builtin_amdgcn_sched_barrier(0);
; #pragma unroll
;                 for (int i = 0; i < 2; ++i) gv[i] = *(const u32x4*)(vg + (size_t)i * 64 * M_TOK + key0 + 64);
;                 bf16x8 vf[4][2];
; #pragma unroll
;                 for (int d = 0; d < 4; ++d)
; #pragma unroll
;                     for (int s2 = 0; s2 < 2; ++s2) vf[d][s2] = *(const LAS bf16x8*)(buf + voff + d * 32 * DA_VP + (16 * s2) * 2);
;                 const float base = slope2 * (float)(key0 + 8 * hh - qpos), b32 = 32.f * slope2;
; #pragma unroll
;                 for (int i = 0; i < 16; ++i) { S0[i] = S0[i] * c1 + cb[i]; S1[i] = S1[i] * c1 + cb[i]; }
;                 float mx = -INFINITY, mx1 = -INFINITY;
; #pragma unroll
;                 for (int i = 0; i < 16; ++i) { mx = fmaxf(mx, S0[i]); mx1 = fmaxf(mx1, S1[i]); }
;                 mx = fmaxf(mx, mx1 + b32) + base;
;                 mx = fmaxf(mx, __shfl_xor(mx, 32));
.LBB0_424:
	s_add_i32 s14, s16, 64
	s_ashr_i32 s15, s14, 31
	s_lshl_b64 s[26:27], s[14:15], 12
	v_lshl_add_u64 v[66:67], v[114:115], 0, s[26:27]
	s_add_i32 s26, s16, 0x60
	s_ashr_i32 s27, s26, 31
	s_lshl_b64 s[26:27], s[26:27], 12
	global_load_dwordx4 v[98:101], v[66:67], off offset:2048
	v_lshl_add_u64 v[66:67], v[114:115], 0, s[26:27]
	global_load_dwordx4 v[102:105], v[66:67], off offset:2048
	s_bitcmp1_b32 s25, 0
	s_cselect_b32 s2, 0x8c00, 0
	s_add_i32 s2, s2, 0
	v_add_u32_e32 v70, s2, v153
	ds_read_b128 v[126:129], v217
	ds_read_b128 v[66:69], v70
	ds_read_b128 v[130:133], v217 offset:1024
	ds_read_b128 v[82:85], v70 offset:32
	ds_read_b128 v[134:137], v217 offset:2048
	ds_read_b128 v[86:89], v70 offset:64
	ds_read_b128 v[138:141], v217 offset:3072
	ds_read_b128 v[90:93], v70 offset:96
	ds_read_b128 v[94:97], v70 offset:8704
	ds_read_b128 v[106:109], v70 offset:8736
	ds_read_b128 v[110:113], v70 offset:8768
	ds_read_b128 v[122:125], v70 offset:8800
	v_mov_b32_e32 v121, v159
	v_mov_b32_e32 v0, v218
	s_waitcnt lgkmcnt(10)
	v_mfma_f32_32x32x16_bf16 v[66:81], v[66:69], v[126:129], 0
	s_ashr_i32 s17, s16, 31
	s_mov_b32 s3, 0x400000
	v_add_u32_e32 v118, s16, v120
	v_add_u32_e32 v191, s2, v211
	s_waitcnt lgkmcnt(8)
	v_mfma_f32_32x32x16_bf16 v[66:81], v[82:85], v[130:133], v[66:81]
	s_waitcnt lgkmcnt(6)
	v_mfma_f32_32x32x16_bf16 v[66:81], v[86:89], v[134:137], v[66:81]
	s_waitcnt lgkmcnt(4)
	v_mfma_f32_32x32x16_bf16 v[66:81], v[90:93], v[138:141], v[66:81]
	s_waitcnt lgkmcnt(3)
	v_mfma_f32_32x32x16_bf16 v[82:97], v[94:97], v[126:129], 0
	s_nop 10
	v_fmamk_f32 v127, v66, 0x3e38aa3b, v192
	v_max_f32_e32 v66, 0xff800000, v127
	v_fmamk_f32 v129, v69, 0x3e38aa3b, v189
	v_fmamk_f32 v159, v74, 0x3e38aa3b, v182
	v_fmamk_f32 v193, v75, 0x3e38aa3b, v183
	v_fmamk_f32 v196, v76, 0x3e38aa3b, v180
	v_cvt_f32_i32_e32 v126, v118
	s_waitcnt lgkmcnt(2)
	v_mfma_f32_32x32x16_bf16 v[82:97], v[106:109], v[130:133], v[82:97]
	v_lshl_add_u64 v[106:107], s[16:17], 1, v[116:117]
	v_add_co_u32_e32 v108, vcc, s3, v106
	v_fmamk_f32 v131, v70, 0x3e38aa3b, v186
	s_nop 0
	v_addc_co_u32_e32 v109, vcc, 0, v107, vcc
	v_fmamk_f32 v133, v71, 0x3e38aa3b, v187
	s_waitcnt lgkmcnt(1)
	v_mfma_f32_32x32x16_bf16 v[82:97], v[110:113], v[134:137], v[82:97]
	global_load_dwordx4 v[110:113], v[106:107], off offset:128
	s_nop 0
	global_load_dwordx4 v[106:109], v[108:109], off offset:128
	v_fmamk_f32 v135, v72, 0x3e38aa3b, v184
	v_fmamk_f32 v137, v73, 0x3e38aa3b, v185
	v_fmamk_f32 v199, v77, 0x3e38aa3b, v181
	v_fmamk_f32 v200, v78, 0x3e38aa3b, v178
	v_fmamk_f32 v204, v79, 0x3e38aa3b, v179
	v_fmamk_f32 v207, v80, 0x3e38aa3b, v176
	s_waitcnt lgkmcnt(0)
	v_mfma_f32_32x32x16_bf16 v[82:97], v[122:125], v[138:141], v[82:97]
	v_fmamk_f32 v123, v67, 0x3e38aa3b, v160
	v_fmamk_f32 v125, v68, 0x3e38aa3b, v188
	v_max3_f32 v66, v66, v123, v125
	v_max3_f32 v66, v66, v129, v131
	v_max3_f32 v66, v66, v133, v135
	v_max3_f32 v66, v66, v137, v159
	v_max3_f32 v66, v66, v193, v196
	s_nop 4
	v_fmamk_f32 v122, v82, 0x3e38aa3b, v192
	v_fmamk_f32 v124, v83, 0x3e38aa3b, v160
	v_fmamk_f32 v128, v84, 0x3e38aa3b, v188
	v_fmamk_f32 v130, v85, 0x3e38aa3b, v189
	v_max3_f32 v67, v122, s54, v124
	v_fmamk_f32 v132, v86, 0x3e38aa3b, v186
	v_fmamk_f32 v134, v87, 0x3e38aa3b, v187
	v_max3_f32 v67, v67, v128, v130
	v_fmamk_f32 v136, v88, 0x3e38aa3b, v184
	v_fmamk_f32 v143, v89, 0x3e38aa3b, v185
	v_max3_f32 v67, v67, v132, v134
	v_fmamk_f32 v169, v90, 0x3e38aa3b, v182
	v_fmamk_f32 v195, v91, 0x3e38aa3b, v183
	v_max3_f32 v67, v67, v136, v143
	v_fmamk_f32 v198, v92, 0x3e38aa3b, v180
	v_fmamk_f32 v202, v93, 0x3e38aa3b, v181
	v_max3_f32 v67, v67, v169, v195
	v_fmamk_f32 v203, v94, 0x3e38aa3b, v178
	v_fmamk_f32 v206, v95, 0x3e38aa3b, v179
	v_max3_f32 v67, v67, v198, v202
	v_fmamk_f32 v219, v96, 0x3e38aa3b, v176
	v_fmamk_f32 v222, v97, 0x3e38aa3b, v177
	v_max3_f32 v67, v67, v203, v206
	v_max3_f32 v66, v66, v199, v200
	v_max3_f32 v67, v67, v219, v222
	v_fmamk_f32 v220, v81, 0x3e38aa3b, v177
	v_max3_f32 v66, v66, v204, v207
	v_add_f32_e32 v67, v157, v67
	v_max3_f32 v66, v66, v220, v67
	v_fmac_f32_e32 v66, v160, v126
	v_mov_b32_e32 v67, v66
	s_nop 1
	v_permlane32_swap_b32_e32 v66, v67
	ds_read_b128 v[94:97], v191 offset:17408
	ds_read_b128 v[90:93], v191 offset:17440
	ds_read_b128 v[86:89], v191 offset:22016
	ds_read_b128 v[82:85], v191 offset:22048
	s_waitcnt lgkmcnt(4)
; DI float fexp2(float x) { return __builtin_amdgcn_exp2f(x); }
; DI void diff_attn_phase(int wv, LAS unsigned char* lds, const bf16_t* qk, const bf16_t* vt, bf16_t* ob, const float* lq1, const float* lk1, const float* lq2, const float* lk2,
;                         const float* subg, int layer_idx) {
;     ...
;                 {
;                     const float mn = fmaxf(m, mx), alpha = fexp2(m - mn); m = mn; l *= alpha;
; #pragma unroll
;                     for (int d = 0; d < 4; ++d) O[d] = O[d] * alpha;
;                 }
;                 const float off = base - m, off1 = off + b32;
;                 float ps = 0.f;
; #pragma unroll
;                 for (int i = 0; i < 16; ++i) { S0[i] = fexp2(S0[i] + off); S1[i] = fexp2(S1[i] + off1); ps += S0[i] + S1[i]; }
;                 l += ps;
;                 const bf16x8 p0 = pack8(S0, 0), p1 = pack8(S0, 1), p2 = pack8(S1, 0), p3 = pack8(S1, 1);
	v_max3_f32 v218, v0, v66, v67
	v_sub_f32_e32 v0, v0, v218
	v_fma_f32 v126, v160, v126, -v218
	v_exp_f32_e32 v118, v0
	v_add_f32_e32 v223, v157, v126
	v_add_f32_e32 v0, v127, v126
	v_exp_f32_e32 v127, v0
	v_add_f32_e32 v0, v122, v223
	v_add_f32_e32 v122, v125, v126
	v_exp_f32_e32 v224, v0
	v_add_f32_e32 v0, v123, v126
	v_exp_f32_e32 v123, v122
	v_add_f32_e32 v122, v128, v223
	v_exp_f32_e32 v225, v122
	v_add_f32_e32 v122, v129, v126
	v_exp_f32_e32 v140, v122
	v_add_f32_e32 v122, v130, v223
	v_exp_f32_e32 v142, v122
	v_add_f32_e32 v122, v133, v126
	v_exp_f32_e32 v144, v122
	v_add_f32_e32 v122, v134, v223
	v_exp_f32_e32 v168, v122
	v_add_f32_e32 v122, v137, v126
	v_exp_f32_e32 v170, v122
	v_add_f32_e32 v122, v143, v223
	v_add_f32_e32 v129, v169, v223
	v_exp_f32_e32 v194, v122
	v_add_f32_e32 v122, v193, v126
	v_exp_f32_e32 v134, v129
	v_add_f32_e32 v129, v196, v126
	v_exp_f32_e32 v196, v122
	v_add_f32_e32 v122, v195, v223
	v_add_f32_e32 v125, v132, v223
	v_add_f32_e32 v130, v198, v223
	v_exp_f32_e32 v198, v122
	v_add_f32_e32 v122, v199, v126
	v_exp_f32_e32 v132, v125
	v_add_f32_e32 v125, v135, v126
	v_exp_f32_e32 v135, v130
	v_add_f32_e32 v130, v200, v126
	v_exp_f32_e32 v200, v122
	v_add_f32_e32 v122, v202, v223
	v_exp_f32_e32 v202, v122
	v_add_f32_e32 v122, v204, v126
	ds_read_b128 v[78:81], v191 offset:26624
	ds_read_b128 v[74:77], v191 offset:26656
	ds_read_b128 v[70:73], v191 offset:31232
	ds_read_b128 v[66:69], v191 offset:31264
	v_exp_f32_e32 v204, v122
	v_add_f32_e32 v122, v206, v223
	v_exp_f32_e32 v138, v0
	v_add_f32_e32 v0, v124, v223
	v_add_f32_e32 v124, v131, v126
	v_add_f32_e32 v128, v136, v223
	v_add_f32_e32 v131, v203, v223
	v_exp_f32_e32 v206, v122
	v_add_f32_e32 v122, v220, v126
	v_exp_f32_e32 v133, v128
	v_add_f32_e32 v128, v159, v126
	v_exp_f32_e32 v136, v131
	v_add_f32_e32 v131, v207, v126
	v_add_f32_e32 v137, v219, v223
	v_exp_f32_e32 v220, v122
	v_add_f32_e32 v122, v222, v223
	v_exp_f32_e32 v0, v0
	v_exp_f32_e32 v124, v124
	v_exp_f32_e32 v125, v125
	v_exp_f32_e32 v128, v128
	v_exp_f32_e32 v129, v129
	v_exp_f32_e32 v130, v130
	v_exp_f32_e32 v131, v131
	v_exp_f32_e32 v137, v137
	v_exp_f32_e32 v222, v122
	v_pk_mul_f32 v[64:65], v[64:65], v[118:119] op_sel_hi:[1,0]
	v_pk_mul_f32 v[62:63], v[62:63], v[118:119] op_sel_hi:[1,0]
	v_pk_mul_f32 v[60:61], v[60:61], v[118:119] op_sel_hi:[1,0]
	v_pk_mul_f32 v[58:59], v[58:59], v[118:119] op_sel_hi:[1,0]
	v_pk_mul_f32 v[56:57], v[56:57], v[118:119] op_sel_hi:[1,0]
	v_pk_mul_f32 v[54:55], v[54:55], v[118:119] op_sel_hi:[1,0]
	v_pk_mul_f32 v[52:53], v[52:53], v[118:119] op_sel_hi:[1,0]
	v_pk_mul_f32 v[50:51], v[50:51], v[118:119] op_sel_hi:[1,0]
	v_pk_mul_f32 v[48:49], v[48:49], v[118:119] op_sel_hi:[1,0]
	v_pk_mul_f32 v[46:47], v[46:47], v[118:119] op_sel_hi:[1,0]
	v_pk_mul_f32 v[44:45], v[44:45], v[118:119] op_sel_hi:[1,0]
	v_pk_mul_f32 v[42:43], v[42:43], v[118:119] op_sel_hi:[1,0]
	v_pk_mul_f32 v[40:41], v[40:41], v[118:119] op_sel_hi:[1,0]
	v_pk_mul_f32 v[38:39], v[38:39], v[118:119] op_sel_hi:[1,0]
	v_pk_mul_f32 v[36:37], v[36:37], v[118:119] op_sel_hi:[1,0]
	v_pk_mul_f32 v[34:35], v[34:35], v[118:119] op_sel_hi:[1,0]
	v_pk_mul_f32 v[32:33], v[32:33], v[118:119] op_sel_hi:[1,0]
	v_pk_mul_f32 v[30:31], v[30:31], v[118:119] op_sel_hi:[1,0]
	v_pk_mul_f32 v[28:29], v[28:29], v[118:119] op_sel_hi:[1,0]
	v_pk_mul_f32 v[26:27], v[26:27], v[118:119] op_sel_hi:[1,0]
	v_pk_mul_f32 v[24:25], v[24:25], v[118:119] op_sel_hi:[1,0]
	v_pk_mul_f32 v[22:23], v[22:23], v[118:119] op_sel_hi:[1,0]
	v_pk_mul_f32 v[20:21], v[20:21], v[118:119] op_sel_hi:[1,0]
	v_pk_mul_f32 v[18:19], v[18:19], v[118:119] op_sel_hi:[1,0]
	v_pk_mul_f32 v[16:17], v[16:17], v[118:119] op_sel_hi:[1,0]
	v_pk_mul_f32 v[14:15], v[14:15], v[118:119] op_sel_hi:[1,0]
	v_pk_mul_f32 v[12:13], v[12:13], v[118:119] op_sel_hi:[1,0]
	v_pk_mul_f32 v[10:11], v[10:11], v[118:119] op_sel_hi:[1,0]
	v_pk_mul_f32 v[8:9], v[8:9], v[118:119] op_sel_hi:[1,0]
	v_pk_mul_f32 v[6:7], v[6:7], v[118:119] op_sel_hi:[1,0]
	v_pk_mul_f32 v[4:5], v[4:5], v[118:119] op_sel_hi:[1,0]
	v_pk_mul_f32 v[2:3], v[2:3], v[118:119] op_sel_hi:[1,0]
	v_add_f32_e32 v139, v127, v224
	v_add_f32_e32 v141, v123, v225
	v_add_f32_e32 v145, v124, v132
	v_add_f32_e32 v171, v125, v133
	v_add_f32_e32 v197, v128, v134
	v_add_f32_e32 v201, v129, v135
	v_add_f32_e32 v205, v130, v136
	v_add_f32_e32 v221, v131, v137
	v_cvt_pk_bf16_f32 v122, v127, v138
	v_cvt_pk_bf16_f32 v123, v123, v140
	v_cvt_pk_bf16_f32 v124, v124, v144
	v_cvt_pk_bf16_f32 v125, v125, v170
	v_cvt_pk_bf16_f32 v126, v128, v196
	v_cvt_pk_bf16_f32 v127, v129, v200
	v_cvt_pk_bf16_f32 v128, v130, v204
	v_cvt_pk_bf16_f32 v129, v131, v220
	v_cvt_pk_bf16_f32 v130, v224, v0
	v_cvt_pk_bf16_f32 v131, v225, v142
	v_cvt_pk_bf16_f32 v132, v132, v168
	v_cvt_pk_bf16_f32 v133, v133, v194
	v_cvt_pk_bf16_f32 v134, v134, v198
	v_cvt_pk_bf16_f32 v135, v135, v202
	v_cvt_pk_bf16_f32 v136, v136, v206
	v_cvt_pk_bf16_f32 v137, v137, v222
	s_waitcnt lgkmcnt(5)
; #define LAS __attribute__((address_space(3)))
; #define MFMA32(a, b, c) __builtin_amdgcn_mfma_f32_32x32x16_bf16((a), (b), (c), 0, 0, 0)
; DI void diff_attn_phase(int wv, LAS unsigned char* lds, const bf16_t* qk, const bf16_t* vt, bf16_t* ob, const float* lq1, const float* lk1, const float* lq2, const float* lk2,
;                         const float* subg, int layer_idx) {
;     ...
;                 for (int d = 0; d < 4; ++d) { O[d] = MFMA32(vf[d][0], p0, O[d]); O[d] = MFMA32(vf[d][1], p1, O[d]); }
;                 __builtin_amdgcn_sched_barrier(0);
; #pragma unroll
;                 for (int d = 0; d < 4; ++d)
; #pragma unroll
;                     for (int s2 = 0; s2 < 2; ++s2) vf[d][s2] = *(const LAS bf16x8*)(buf + voff + d * 32 * DA_VP + (32 + 16 * s2) * 2);
; #pragma unroll
;                 for (int d = 0; d < 4; ++d) { O[d] = MFMA32(vf[d][0], p2, O[d]); O[d] = MFMA32(vf[d][1], p3, O[d]); }
;             }
;             if (more) {
;                 LAS unsigned char* nb = lds + ((t + 1) & 1) * DA_BUF;
; #pragma unroll
;                 for (int i = 0; i < 2; ++i) { *(LAS u32x4*)(nb + kst_off + i * 32 * DA_KP) = gk[i]; *(LAS u32x4*)(nb + vst_off + i * 64 * DA_VP) = gv[i]; } }
;             __syncthreads();
	v_mfma_f32_32x32x16_bf16 v[34:49], v[86:89], v[122:125], v[34:49]
	s_waitcnt lgkmcnt(4)
	v_mfma_f32_32x32x16_bf16 v[34:49], v[82:85], v[126:129], v[34:49]
	v_add_f32_e64 v82, v138, v0
	v_add_f32_e64 v83, v139, v1
	s_waitcnt lgkmcnt(3)
	v_mfma_f32_32x32x16_bf16 v[18:33], v[78:81], v[122:125], v[18:33]
	v_add_f32_e64 v78, v82, v82
	v_add_f32_e64 v79, v82, v83
	v_mov_b32_e32 v143, v79
	v_add_f32_e64 v78, v140, v142
	v_add_f32_e64 v79, v141, v143
	v_pk_add_f32 v[78:79], v[78:79], v[78:79] op_sel_hi:[0,1]
	v_mov_b32_e32 v169, v79
	v_pk_add_f32 v[78:79], v[144:145], v[168:169]
	v_mfma_f32_32x32x16_bf16 v[50:65], v[94:97], v[122:125], v[50:65]
	v_pk_add_f32 v[78:79], v[78:79], v[78:79] op_sel_hi:[0,1]
	v_mov_b32_e32 v195, v79
	s_waitcnt lgkmcnt(1)
	v_mfma_f32_32x32x16_bf16 v[2:17], v[70:73], v[122:125], v[2:17]
	v_mfma_f32_32x32x16_bf16 v[18:33], v[74:77], v[126:129], v[18:33]
	v_add_f32_e64 v74, v170, v194
	v_add_f32_e64 v75, v171, v195
	v_pk_add_f32 v[74:75], v[74:75], v[74:75] op_sel_hi:[0,1]
	v_mov_b32_e32 v199, v75
	v_pk_add_f32 v[74:75], v[196:197], v[198:199]
	s_nop 0
	v_pk_add_f32 v[74:75], v[74:75], v[74:75] op_sel_hi:[0,1]
	v_mov_b32_e32 v203, v75
	v_mfma_f32_32x32x16_bf16 v[50:65], v[90:93], v[126:129], v[50:65]
	v_add_f32_e64 v70, v200, v202
	v_add_f32_e64 v71, v201, v203
	v_pk_add_f32 v[70:71], v[70:71], v[70:71] op_sel_hi:[0,1]
	v_mov_b32_e32 v207, v71
	v_pk_add_f32 v[70:71], v[204:205], v[206:207]
	s_nop 0
	v_pk_add_f32 v[70:71], v[70:71], v[70:71] op_sel_hi:[0,1]
	s_waitcnt lgkmcnt(0)
	v_mfma_f32_32x32x16_bf16 v[2:17], v[66:69], v[126:129], v[2:17]
	v_mov_b32_e32 v223, v71
	v_add_f32_e64 v70, v220, v222
	v_add_f32_e64 v71, v221, v223
	v_add_f32_e32 v159, v70, v71
	ds_read_b128 v[66:69], v191 offset:17472
	ds_read_b128 v[70:73], v191 offset:17504
	ds_read_b128 v[78:81], v191 offset:22080
	ds_read_b128 v[82:85], v191 offset:22112
	ds_read_b128 v[86:89], v191 offset:26688
	ds_read_b128 v[90:93], v191 offset:26720
	ds_read_b128 v[94:97], v191 offset:31296
	ds_read_b128 v[74:77], v191 offset:31328
	s_add_i32 s25, s25, 1
	s_bitcmp1_b32 s25, 0
	s_cselect_b32 s2, 0x8c00, 0
	s_add_i32 s2, s2, 0
	v_add_u32_e32 v0, s2, v167
	v_add_u32_e32 v223, s2, v208
	v_fmac_f32_e32 v159, v121, v118
	s_cmp_eq_u32 s1, s25
	s_mov_b32 s16, s14
	s_waitcnt vmcnt(2)
	ds_write_b128 v0, v[98:101]
	ds_write_b128 v0, v[102:105] offset:8704
	s_waitcnt lgkmcnt(9)
	v_mfma_f32_32x32x16_bf16 v[50:65], v[66:69], v[130:133], v[50:65]
	s_waitcnt lgkmcnt(8)
	v_mfma_f32_32x32x16_bf16 v[50:65], v[70:73], v[134:137], v[50:65]
	s_waitcnt lgkmcnt(7)
	v_mfma_f32_32x32x16_bf16 v[34:49], v[78:81], v[130:133], v[34:49]
	s_waitcnt lgkmcnt(6)
	v_mfma_f32_32x32x16_bf16 v[34:49], v[82:85], v[134:137], v[34:49]
	s_waitcnt lgkmcnt(5)
	v_mfma_f32_32x32x16_bf16 v[18:33], v[86:89], v[130:133], v[18:33]
	s_waitcnt lgkmcnt(4)
	v_mfma_f32_32x32x16_bf16 v[18:33], v[90:93], v[134:137], v[18:33]
	s_waitcnt lgkmcnt(3)
	v_mfma_f32_32x32x16_bf16 v[2:17], v[94:97], v[130:133], v[2:17]
	s_waitcnt vmcnt(0)
	ds_write_b128 v223, v[110:113] offset:17408
	ds_write_b128 v223, v[106:109] offset:26624
	s_waitcnt lgkmcnt(0)
	s_barrier
	v_mfma_f32_32x32x16_bf16 v[2:17], v[74:77], v[134:137], v[2:17]
	s_cbranch_scc0 .LBB0_424
	s_branch .LBB0_427
